# Y (down-GEMM output) stored with each rows 128-byte lines rotated by row mod 16 to spread epilogue stores over L2 channels; generated plain Y epilogue; row loops read the rotated layout
# baseline (speedup 1.0000x reference)
; __device__ __forceinline__ float h_lo(unsigned w) { return (float)__builtin_bit_cast(h16x2, w).x; }
; __device__ __forceinline__ float h_hi(unsigned w) { return (float)__builtin_bit_cast(h16x2, w).y; }
; __device__ __forceinline__ void rows_one(CP pp, int mode, int r, int has_pre, const f32x4 (&gg)[4], const f32x4 (&pa)[4], const f32x4 (&pb)[4], int lane) {
;     ...
;         const u32x2* yr = (const u32x2*)((const bf16_t*)(pp->ws + WS_Y) + (size_t)r * D) + lane;
;         f32x4 y[4]; float ss = 0.f;
; #pragma unroll
;         for (int j = 0; j < 4; ++j) { const u32x2 w = __builtin_nontemporal_load(yr + 64 * j); const u32x2 xw_ = __builtin_nontemporal_load(xrow + 64 * j); v[j] = (f32x4){h_lo(xw_.x), h_hi(xw_.x), h_lo(xw_.y), h_hi(xw_.y)}; y[j] = (f32x4){bf_lo(w.x), bf_hi(w.x), bf_lo(w.y), bf_hi(w.y)}; ss += (y[j][0] * y[j][0] + y[j][1] * y[j][1]) + (y[j][2] * y[j][2] + y[j][3] * y[j][3]); }
;         const float rstd = 1.0f / sqrtf(wave_sum(ss) * (1.0f / D) + EPS);
; #pragma unroll
;         for (int j = 0; j < 4; ++j) v[j] = v[j] + gg[j] * (y[j] * rstd);
;     }
;     if (has_pre) {
; #pragma unroll
;         for (int j = 0; j < 4; ++j) { u32x2 w; w.x = pk2h(v[j][0], v[j][1]); w.y = pk2h(v[j][2], v[j][3]); __builtin_nontemporal_store(w, xrow + 64 * j); }
.LBB0_351:
	v_add_u32_e32 v70, v87, v86
	v_ashrrev_i32_e32 v71, 31, v70
	v_lshlrev_b64 v[16:17], 11, v[70:71]
	v_mov_b32_e32 v112, v70
	v_lshrrev_b32_e32 v110, 4, v85
	v_add_u32_e32 v110, v110, v112
	v_and_b32_e32 v111, 15, v85
	v_lshlrev_b32_e32 v111, 3, v111
	v_lshl_or_b32 v111, v112, 11, v111
	v_add_u32_e32 v113, 0, v110
	v_and_b32_e32 v113, 15, v113
	v_lshl_or_b32 v113, v113, 7, v111
	global_load_dwordx2 v[20:21], v113, s[64:65] nt
	v_add_u32_e32 v113, 4, v110
	v_and_b32_e32 v113, 15, v113
	v_lshl_or_b32 v113, v113, 7, v111
	global_load_dwordx2 v[22:23], v113, s[64:65] nt
	v_add_u32_e32 v113, 8, v110
	v_and_b32_e32 v113, 15, v113
	v_lshl_or_b32 v113, v113, 7, v111
	global_load_dwordx2 v[24:25], v113, s[64:65] nt
	v_add_u32_e32 v113, 12, v110
	v_and_b32_e32 v113, 15, v113
	v_lshl_or_b32 v113, v113, 7, v111
	global_load_dwordx2 v[26:27], v113, s[64:65] nt
	v_lshl_add_u64 v[72:73], v[64:65], 0, v[16:17]
	global_load_dwordx2 v[80:81], v[72:73], off nt
	global_load_dwordx2 v[76:77], v[72:73], off offset:512 nt
	global_load_dwordx2 v[30:31], v[72:73], off offset:1024 nt
	global_load_dwordx2 v[78:79], v[72:73], off offset:1536 nt
	s_waitcnt vmcnt(7)
	v_and_b32_e32 v17, 0xffff0000, v20
	v_and_b32_e32 v19, 0xffff0000, v21
	v_lshlrev_b32_e32 v16, 16, v20
	v_lshlrev_b32_e32 v18, 16, v21
	s_waitcnt vmcnt(6)
	v_lshlrev_b32_e32 v75, 16, v23
	v_and_b32_e32 v21, 0xffff0000, v23
	v_and_b32_e32 v20, 0xffff0000, v22
	s_waitcnt vmcnt(5)
	v_and_b32_e32 v23, 0xffff0000, v24
	s_waitcnt vmcnt(4)
	v_lshlrev_b32_e32 v83, 16, v26
	v_and_b32_e32 v29, 0xffff0000, v26
	v_mul_f32_e32 v28, v19, v19
	v_mul_f32_e32 v82, v17, v17
	v_lshlrev_b32_e32 v74, 16, v22
	v_lshlrev_b32_e32 v22, 16, v24
	v_lshlrev_b32_e32 v24, 16, v25
	v_and_b32_e32 v25, 0xffff0000, v25
	v_pk_mul_f32 v[94:95], v[20:21], v[20:21]
	v_mov_b32_e32 v97, v83
	v_mul_f32_e32 v96, v23, v23
	v_pk_fma_f32 v[100:101], v[18:19], v[18:19], v[28:29] op_sel_hi:[1,1,0]
	v_pk_fma_f32 v[102:103], v[16:17], v[16:17], v[82:83] op_sel_hi:[1,1,0]
	v_lshlrev_b32_e32 v26, 16, v27
	v_and_b32_e32 v27, 0xffff0000, v27
	v_mul_f32_e32 v98, v25, v25
	v_pk_fma_f32 v[94:95], v[74:75], v[74:75], v[94:95]
	v_pk_fma_f32 v[104:105], v[22:23], v[22:23], v[96:97] op_sel_hi:[1,1,0]
	v_mov_b32_e32 v82, v102
	v_mov_b32_e32 v96, v100
	v_mul_f32_e32 v106, v29, v29
	v_mul_f32_e32 v107, v26, v26
	v_mul_f32_e32 v108, v27, v27
	v_pk_fma_f32 v[98:99], v[24:25], v[24:25], v[98:99] op_sel_hi:[1,1,0]
	v_pk_add_f32 v[100:101], v[102:103], v[100:101]
	v_pk_add_f32 v[94:95], v[94:95], v[94:95] op_sel:[0,1] op_sel_hi:[1,0]
	v_pk_mul_f32 v[96:97], v[82:83], v[96:97]
	v_mov_b32_e32 v105, v107
	v_mov_b32_e32 v99, v108
	v_mov_b32_e32 v95, v106
	v_mov_b32_e32 v101, v97
	v_pk_add_f32 v[98:99], v[104:105], v[98:99]
	v_pk_add_f32 v[94:95], v[100:101], v[94:95]
	s_waitcnt vmcnt(1)
	v_cvt_f32_f16_e32 v100, v31
	v_pk_add_f32 v[94:95], v[94:95], v[98:99]
	v_cvt_f32_f16_e32 v98, v30
	v_add_f32_e32 v28, v94, v95
	ds_bpermute_b32 v82, v88, v28
	v_cvt_f32_f16_sdwa v99, v30 dst_sel:DWORD dst_unused:UNUSED_PAD src0_sel:WORD_1
	v_cvt_f32_f16_sdwa v101, v31 dst_sel:DWORD dst_unused:UNUSED_PAD src0_sel:WORD_1
	v_mov_b32_e32 v31, v20
	v_mov_b32_e32 v20, v75
	s_waitcnt lgkmcnt(0)
	v_add_f32_e32 v28, v28, v82
	ds_bpermute_b32 v82, v89, v28
	v_cndmask_b32_e64 v94, 0, 1, s[68:69]
	v_cmp_ne_u32_e64 s[8:9], 1, v94
	v_cvt_f32_f16_e32 v94, v80
	v_cvt_f32_f16_sdwa v95, v80 dst_sel:DWORD dst_unused:UNUSED_PAD src0_sel:WORD_1
	s_waitcnt lgkmcnt(0)
	v_add_f32_e32 v28, v28, v82
	ds_bpermute_b32 v82, v90, v28
	v_cvt_f32_f16_e32 v80, v81
	v_cvt_f32_f16_sdwa v81, v81 dst_sel:DWORD dst_unused:UNUSED_PAD src0_sel:WORD_1
	v_cvt_f32_f16_e32 v96, v76
	v_cvt_f32_f16_sdwa v97, v76 dst_sel:DWORD dst_unused:UNUSED_PAD src0_sel:WORD_1
	s_waitcnt lgkmcnt(0)
	v_add_f32_e32 v28, v28, v82
	ds_bpermute_b32 v82, v91, v28
	v_cvt_f32_f16_e32 v76, v77
	v_cvt_f32_f16_sdwa v77, v77 dst_sel:DWORD dst_unused:UNUSED_PAD src0_sel:WORD_1
	s_waitcnt vmcnt(0)
	v_cvt_f32_f16_e32 v102, v78
	v_cvt_f32_f16_sdwa v103, v78 dst_sel:DWORD dst_unused:UNUSED_PAD src0_sel:WORD_1
	s_waitcnt lgkmcnt(0)
	v_add_f32_e32 v28, v28, v82
	ds_bpermute_b32 v82, v92, v28
	v_cvt_f32_f16_e32 v78, v79
	v_cvt_f32_f16_sdwa v79, v79 dst_sel:DWORD dst_unused:UNUSED_PAD src0_sel:WORD_1
	s_waitcnt lgkmcnt(0)
	v_add_f32_e32 v28, v28, v82
	ds_bpermute_b32 v30, v93, v28
	s_waitcnt lgkmcnt(0)
	v_add_f32_e32 v28, v28, v30
	v_fmamk_f32 v28, v28, 0x3a800000, v165
	v_mul_f32_e32 v30, 0x4f800000, v28
	v_cmp_gt_f32_e32 vcc, s44, v28
	s_nop 1
	v_cndmask_b32_e32 v28, v28, v30, vcc
	v_sqrt_f32_e32 v82, v28
	v_mov_b32_e32 v30, v74
	v_add_u32_e32 v74, -1, v82
	v_add_u32_e32 v75, 1, v82
	v_fma_f32 v104, -v74, v82, v28
	v_fma_f32 v105, -v75, v82, v28
	v_cmp_ge_f32_e64 s[10:11], 0, v104
	s_nop 1
	v_cndmask_b32_e64 v74, v82, v74, s[10:11]
	v_cmp_lt_f32_e64 s[10:11], 0, v105
	s_nop 1
	v_cndmask_b32_e64 v74, v74, v75, s[10:11]
	v_mul_f32_e32 v75, 0x37800000, v74
	v_cndmask_b32_e32 v74, v74, v75, vcc
	v_cmp_class_f32_e32 vcc, v28, v167
	s_nop 1
	v_cndmask_b32_e32 v74, v74, v28, vcc
	v_div_scale_f32 v75, s[10:11], v74, v74, 1.0
	v_rcp_f32_e32 v82, v75
	v_mov_b32_e32 v28, v83
	v_div_scale_f32 v83, vcc, 1.0, v74, 1.0
	v_fma_f32 v104, -v75, v82, 1.0
	v_fmac_f32_e32 v82, v104, v82
	v_mul_f32_e32 v104, v83, v82
	v_fma_f32 v105, -v75, v104, v83
	v_fmac_f32_e32 v104, v105, v82
	v_fma_f32 v75, -v75, v104, v83
	v_div_fmas_f32 v75, v75, v82, v104
	v_div_fixup_f32 v74, v75, v74, 1.0
	v_pk_mul_f32 v[16:17], v[74:75], v[16:17] op_sel_hi:[0,1]
	v_pk_mul_f32 v[18:19], v[74:75], v[18:19] op_sel_hi:[0,1]
	v_pk_mul_f32 v[82:83], v[74:75], v[30:31] op_sel_hi:[0,1]
	v_pk_mul_f32 v[20:21], v[74:75], v[20:21] op_sel_hi:[0,1]
	v_pk_mul_f32 v[104:105], v[74:75], v[22:23] op_sel_hi:[0,1]
	v_pk_mul_f32 v[22:23], v[74:75], v[24:25] op_sel_hi:[0,1]
	v_pk_mul_f32 v[106:107], v[28:29], v[74:75] op_sel_hi:[1,0]
	v_pk_mul_f32 v[74:75], v[26:27], v[74:75] op_sel_hi:[1,0]
	s_andn2_b64 vcc, exec, s[68:69]
	v_pk_fma_f32 v[30:31], v[40:41], v[18:19], v[80:81]
	v_pk_fma_f32 v[28:29], v[42:43], v[16:17], v[94:95]
	v_pk_fma_f32 v[26:27], v[32:33], v[20:21], v[76:77]
	v_pk_fma_f32 v[24:25], v[34:35], v[82:83], v[96:97]
	v_pk_fma_f32 v[22:23], v[36:37], v[22:23], v[100:101]
	v_pk_fma_f32 v[20:21], v[38:39], v[104:105], v[98:99]
	v_pk_fma_f32 v[18:19], v[44:45], v[74:75], v[78:79]
	v_pk_fma_f32 v[16:17], v[46:47], v[106:107], v[102:103]
	s_mov_b64 s[10:11], -1
	s_cbranch_vccnz .LBB0_354
	v_cvt_pk_f16_f32 v74, v28, v29
	v_cvt_pk_f16_f32 v75, v30, v31
	global_store_dwordx2 v[72:73], v[74:75], off nt
	v_cvt_pk_f16_f32 v74, v24, v25
	v_cvt_pk_f16_f32 v75, v26, v27
	global_store_dwordx2 v[72:73], v[74:75], off offset:512 nt
	v_cvt_pk_f16_f32 v74, v20, v21
	v_cvt_pk_f16_f32 v75, v22, v23
	global_store_dwordx2 v[72:73], v[74:75], off offset:1024 nt
	v_cvt_pk_f16_f32 v74, v16, v17
	v_cvt_pk_f16_f32 v75, v18, v19
	global_store_dwordx2 v[72:73], v[74:75], off offset:1536 nt
	v_lshlrev_b64 v[70:71], 10, v[70:71]
	s_cbranch_execz .LBB0_355

; __device__ __forceinline__ float h_lo(unsigned w) { return (float)__builtin_bit_cast(h16x2, w).x; }
; __device__ __forceinline__ float h_hi(unsigned w) { return (float)__builtin_bit_cast(h16x2, w).y; }
; __device__ __forceinline__ void rows_one(CP pp, int mode, int r, int has_pre, const f32x4 (&gg)[4], const f32x4 (&pa)[4], const f32x4 (&pb)[4], int lane) {
;     ...
;         const u32x2* yr = (const u32x2*)((const bf16_t*)(pp->ws + WS_Y) + (size_t)r * D) + lane;
;         f32x4 y[4]; float ss = 0.f;
; #pragma unroll
;         for (int j = 0; j < 4; ++j) { const u32x2 w = __builtin_nontemporal_load(yr + 64 * j); const u32x2 xw_ = __builtin_nontemporal_load(xrow + 64 * j); v[j] = (f32x4){h_lo(xw_.x), h_hi(xw_.x), h_lo(xw_.y), h_hi(xw_.y)}; y[j] = (f32x4){bf_lo(w.x), bf_hi(w.x), bf_lo(w.y), bf_hi(w.y)}; ss += (y[j][0] * y[j][0] + y[j][1] * y[j][1]) + (y[j][2] * y[j][2] + y[j][3] * y[j][3]); }
;         const float rstd = 1.0f / sqrtf(wave_sum(ss) * (1.0f / D) + EPS);
; #pragma unroll
;         for (int j = 0; j < 4; ++j) v[j] = v[j] + gg[j] * (y[j] * rstd);
;     }
;     if (has_pre) {
; #pragma unroll
;         for (int j = 0; j < 4; ++j) { u32x2 w; w.x = pk2h(v[j][0], v[j][1]); w.y = pk2h(v[j][2], v[j][3]); __builtin_nontemporal_store(w, xrow + 64 * j); }
; __device__ __forceinline__ void phase_rows(CP pp, int mode, int rows, int li, int k, float wgt, int has_pre, int li2, int k2) {
;     ...
;         rows_vectors(pp, mode, 8, li, k, wgt, has_pre, li2, k2, gg, pa, pb, lane);
;         for (int rc = gw; rc < NCTX; rc += NGW) rows_one(pp, mode, NLAT + rc, has_pre, gg, pa, pb, lane);
.LBB0_363:
	v_add_u32_e32 v112, 0x10000, v84
	v_lshrrev_b32_e32 v110, 4, v85
	v_add_u32_e32 v110, v110, v112
	v_and_b32_e32 v111, 15, v85
	v_lshlrev_b32_e32 v111, 3, v111
	v_lshl_or_b32 v111, v112, 11, v111
	v_add_u32_e32 v113, 0, v110
	v_and_b32_e32 v113, 15, v113
	v_lshl_or_b32 v113, v113, 7, v111
	global_load_dwordx2 v[18:19], v113, s[64:65] nt
	v_add_u32_e32 v113, 4, v110
	v_and_b32_e32 v113, 15, v113
	v_lshl_or_b32 v113, v113, 7, v111
	global_load_dwordx2 v[20:21], v113, s[64:65] nt
	v_add_u32_e32 v113, 8, v110
	v_and_b32_e32 v113, 15, v113
	v_lshl_or_b32 v113, v113, 7, v111
	global_load_dwordx2 v[24:25], v113, s[64:65] nt
	v_add_u32_e32 v113, 12, v110
	v_and_b32_e32 v113, 15, v113
	v_lshl_or_b32 v113, v113, 7, v111
	global_load_dwordx2 v[26:27], v113, s[64:65] nt
	v_add_co_u32_e32 v16, vcc, 0x8400000, v66
	s_waitcnt vmcnt(2)
	v_lshlrev_b32_e32 v79, 16, v21
	v_addc_co_u32_e32 v17, vcc, 0, v67, vcc
	global_load_dwordx2 v[28:29], v[16:17], off nt
	global_load_dwordx2 v[30:31], v[16:17], off offset:512 nt
	global_load_dwordx2 v[74:75], v[16:17], off offset:1024 nt
	global_load_dwordx2 v[76:77], v[16:17], off offset:1536 nt
	v_lshlrev_b32_e32 v16, 16, v18
	v_and_b32_e32 v17, 0xffff0000, v18
	v_lshlrev_b32_e32 v18, 16, v19
	v_and_b32_e32 v19, 0xffff0000, v19
	v_lshlrev_b32_e32 v78, 16, v20
	v_and_b32_e32 v21, 0xffff0000, v21
	v_and_b32_e32 v20, 0xffff0000, v20
	s_waitcnt vmcnt(5)
	v_and_b32_e32 v23, 0xffff0000, v24
	s_waitcnt vmcnt(4)
	v_lshlrev_b32_e32 v81, 16, v26
	v_and_b32_e32 v83, 0xffff0000, v26
	v_mul_f32_e32 v80, v19, v19
	v_mul_f32_e32 v82, v17, v17
	v_lshlrev_b32_e32 v22, 16, v24
	v_lshlrev_b32_e32 v24, 16, v25
	v_and_b32_e32 v25, 0xffff0000, v25
	v_pk_mul_f32 v[86:87], v[20:21], v[20:21]
	v_mov_b32_e32 v89, v81
	v_mul_f32_e32 v88, v23, v23
	v_pk_fma_f32 v[92:93], v[18:19], v[18:19], v[80:81] op_sel_hi:[1,1,0]
	v_pk_fma_f32 v[94:95], v[16:17], v[16:17], v[82:83] op_sel_hi:[1,1,0]
	v_lshlrev_b32_e32 v26, 16, v27
	v_and_b32_e32 v27, 0xffff0000, v27
	v_mul_f32_e32 v90, v25, v25
	v_pk_fma_f32 v[86:87], v[78:79], v[78:79], v[86:87]
	v_pk_fma_f32 v[96:97], v[22:23], v[22:23], v[88:89] op_sel_hi:[1,1,0]
	v_mov_b32_e32 v80, v94
	v_mov_b32_e32 v88, v92
	v_mul_f32_e32 v85, v83, v83
	v_mul_f32_e32 v98, v26, v26
	v_mul_f32_e32 v99, v27, v27
	v_pk_fma_f32 v[90:91], v[24:25], v[24:25], v[90:91] op_sel_hi:[1,1,0]
	v_pk_add_f32 v[92:93], v[94:95], v[92:93]
	v_pk_add_f32 v[86:87], v[86:87], v[86:87] op_sel:[0,1] op_sel_hi:[1,0]
	v_pk_mul_f32 v[88:89], v[80:81], v[88:89]
	v_mov_b32_e32 v97, v98
	v_mov_b32_e32 v91, v99
	v_mov_b32_e32 v87, v85
	v_mov_b32_e32 v93, v89
	v_pk_add_f32 v[90:91], v[96:97], v[90:91]
	v_pk_add_f32 v[86:87], v[92:93], v[86:87]
	s_waitcnt vmcnt(2)
	v_cvt_f32_f16_e32 v88, v31
	v_pk_add_f32 v[86:87], v[86:87], v[90:91]
	v_cvt_f32_f16_sdwa v89, v31 dst_sel:DWORD dst_unused:UNUSED_PAD src0_sel:WORD_1
	v_add_f32_e32 v80, v86, v87
	ds_bpermute_b32 v82, v68, v80
	v_mov_b32_e32 v86, v78
	v_mov_b32_e32 v87, v20
	v_mov_b32_e32 v20, v79
	v_cvt_f32_f16_e32 v78, v28
	s_waitcnt lgkmcnt(0)
	v_add_f32_e32 v80, v80, v82
	ds_bpermute_b32 v82, v69, v80
	v_cvt_f32_f16_sdwa v79, v28 dst_sel:DWORD dst_unused:UNUSED_PAD src0_sel:WORD_1
	v_cvt_f32_f16_e32 v28, v29
	v_cvt_f32_f16_sdwa v29, v29 dst_sel:DWORD dst_unused:UNUSED_PAD src0_sel:WORD_1
	s_waitcnt vmcnt(1)
	v_cvt_f32_f16_sdwa v91, v74 dst_sel:DWORD dst_unused:UNUSED_PAD src0_sel:WORD_1
	s_waitcnt lgkmcnt(0)
	v_add_f32_e32 v80, v80, v82
	ds_bpermute_b32 v85, v70, v80
	v_mov_b32_e32 v82, v81
	s_waitcnt vmcnt(0)
	v_cvt_f32_f16_e32 v92, v76
	v_cvt_f32_f16_sdwa v93, v76 dst_sel:DWORD dst_unused:UNUSED_PAD src0_sel:WORD_1
	v_cvt_f32_f16_e32 v76, v77
	s_waitcnt lgkmcnt(0)
	v_add_f32_e32 v80, v80, v85
	ds_bpermute_b32 v81, v71, v80
	v_cvt_f32_f16_sdwa v77, v77 dst_sel:DWORD dst_unused:UNUSED_PAD src0_sel:WORD_1
	s_waitcnt lgkmcnt(0)
	v_add_f32_e32 v85, v80, v81
	ds_bpermute_b32 v90, v72, v85
	v_cvt_f32_f16_e32 v80, v30
	v_cvt_f32_f16_sdwa v81, v30 dst_sel:DWORD dst_unused:UNUSED_PAD src0_sel:WORD_1
	s_waitcnt lgkmcnt(0)
	v_add_f32_e32 v30, v85, v90
	ds_bpermute_b32 v31, v73, v30
	v_cvt_f32_f16_e32 v90, v74
	v_cvt_f32_f16_e32 v74, v75
	v_cvt_f32_f16_sdwa v75, v75 dst_sel:DWORD dst_unused:UNUSED_PAD src0_sel:WORD_1
	s_waitcnt lgkmcnt(0)
	v_add_f32_e32 v30, v30, v31
	v_fmamk_f32 v30, v30, 0x3a800000, v165
	v_mul_f32_e32 v31, 0x4f800000, v30
	v_cmp_gt_f32_e32 vcc, s44, v30
	s_nop 1
	v_cndmask_b32_e32 v30, v30, v31, vcc
	v_sqrt_f32_e32 v31, v30
	s_nop 0
	v_add_u32_e32 v85, -1, v31
	v_add_u32_e32 v94, 1, v31
	v_fma_f32 v95, -v85, v31, v30
	v_fma_f32 v96, -v94, v31, v30
	v_cmp_ge_f32_e64 s[10:11], 0, v95
	s_nop 1
	v_cndmask_b32_e64 v31, v31, v85, s[10:11]
	v_cmp_lt_f32_e64 s[10:11], 0, v96
	s_nop 1
	v_cndmask_b32_e64 v31, v31, v94, s[10:11]
	v_mul_f32_e32 v85, 0x37800000, v31
	v_cndmask_b32_e32 v31, v31, v85, vcc
	v_cmp_class_f32_e32 vcc, v30, v167
	s_mov_b64 s[10:11], -1
	s_nop 0
	v_cndmask_b32_e32 v30, v31, v30, vcc
	v_div_scale_f32 v31, s[4:5], v30, v30, 1.0
	v_rcp_f32_e32 v85, v31
	v_div_scale_f32 v94, vcc, 1.0, v30, 1.0
	v_fma_f32 v95, -v31, v85, 1.0
	v_fmac_f32_e32 v85, v95, v85
	v_mul_f32_e32 v95, v94, v85
	v_fma_f32 v96, -v31, v95, v94
	v_fmac_f32_e32 v95, v96, v85
	v_fma_f32 v31, -v31, v95, v94
	v_div_fmas_f32 v31, v31, v85, v95
	v_div_fixup_f32 v30, v31, v30, 1.0
	v_pk_mul_f32 v[16:17], v[30:31], v[16:17] op_sel_hi:[0,1]
	v_pk_mul_f32 v[18:19], v[30:31], v[18:19] op_sel_hi:[0,1]
	v_pk_mul_f32 v[86:87], v[30:31], v[86:87] op_sel_hi:[0,1]
	v_pk_mul_f32 v[20:21], v[30:31], v[20:21] op_sel_hi:[0,1]
	v_pk_mul_f32 v[94:95], v[30:31], v[22:23] op_sel_hi:[0,1]
	v_pk_mul_f32 v[22:23], v[30:31], v[24:25] op_sel_hi:[0,1]
	v_pk_mul_f32 v[82:83], v[82:83], v[30:31] op_sel_hi:[1,0]
	v_pk_mul_f32 v[96:97], v[26:27], v[30:31] op_sel_hi:[1,0]
	s_and_b64 vcc, exec, s[8:9]
	v_pk_fma_f32 v[30:31], v[40:41], v[18:19], v[28:29]
	v_pk_fma_f32 v[28:29], v[42:43], v[16:17], v[78:79]
	v_pk_fma_f32 v[26:27], v[32:33], v[20:21], v[88:89]
	v_pk_fma_f32 v[24:25], v[34:35], v[86:87], v[80:81]
	v_pk_fma_f32 v[22:23], v[36:37], v[22:23], v[74:75]
	v_pk_fma_f32 v[20:21], v[38:39], v[94:95], v[90:91]
	v_pk_fma_f32 v[18:19], v[44:45], v[96:97], v[76:77]
	v_pk_fma_f32 v[16:17], v[46:47], v[82:83], v[92:93]
	s_cbranch_vccnz .LBB0_366
	s_mov_b64 s[4:5], 0x8400000
	v_lshl_add_u64 v[74:75], v[66:67], 0, s[4:5]
	s_mov_b64 s[4:5], 0x8400200
	v_cvt_pk_f16_f32 v82, v28, v29
	v_cvt_pk_f16_f32 v83, v30, v31
	v_lshl_add_u64 v[76:77], v[66:67], 0, s[4:5]
	s_mov_b64 s[4:5], 0x8400400
	global_store_dwordx2 v[74:75], v[82:83], off nt
	v_cvt_pk_f16_f32 v74, v24, v25
	v_cvt_pk_f16_f32 v75, v26, v27
	v_lshl_add_u64 v[78:79], v[66:67], 0, s[4:5]
	s_mov_b64 s[4:5], 0x8400600
	global_store_dwordx2 v[76:77], v[74:75], off nt
	v_cvt_pk_f16_f32 v74, v20, v21
	v_cvt_pk_f16_f32 v75, v22, v23
	v_lshl_add_u64 v[80:81], v[66:67], 0, s[4:5]
	global_store_dwordx2 v[78:79], v[74:75], off nt
	v_cvt_pk_f16_f32 v74, v16, v17
	v_cvt_pk_f16_f32 v75, v18, v19
	global_store_dwordx2 v[80:81], v[74:75], off nt
	s_cbranch_execz .LBB0_367

; __device__ __forceinline__ unsigned pk2(float lo, float hi) { return pg8::cvt_pk_bf16(lo, hi); }
; __device__ __forceinline__ float gelu_tanh(float x) { const float u = 1.5957691216057308f * (x + 0.044715f * x * x * x); return x * sigmoidf_(u); }
;     __device__ __forceinline__ void operator()(const f32x4 (&acc)[2][2][4][2], const pg8::Unit& u, int wr, int wc, int fr, int fq) const {
;     ...
;         for (int ai = 0; ai < 2; ++ai)
; #pragma unroll
;             for (int m = 0; m < 4; ++m) {
;                 const int row = row0 + ai * 128 + m * 16;
;                 bf16_t* rowp = O + (size_t)row * ldc + col0;
;                 float s = 0.f, ss = 0.f;
; #pragma unroll
;                 for (int bj = 0; bj < 2; ++bj) {
;                     f32x4 v0 = acc[ai][bj][m][0] + bv[bj][0], v1 = acc[ai][bj][m][1] + bv[bj][1];
;                     if (do_gelu) {
; #pragma unroll
;                         for (int e = 0; e < 4; ++e) { v0[e] = gelu_tanh(v0[e]); v1[e] = gelu_tanh(v1[e]); }
;                     }
; #pragma unroll
;                     for (int e = 0; e < 4; ++e) { s += v0[e] + v1[e]; ss += v0[e] * v0[e] + v1[e] * v1[e]; }
;                     u32x4 w; w.x = pk2(v0[0], v0[1]); w.y = pk2(v0[2], v0[3]); w.z = pk2(v1[0], v1[1]); w.w = pk2(v1[2], v1[3]);
;                     *(u32x4*)(rowp + bj * 128) = w;
;                 }
.LBB0_397:
	v_lshl_add_u32 v204, s84, 8, v146
	v_lshl_or_b32 v205, s83, 8, v148
	v_lshlrev_b32_e32 v205, 1, v205
	v_and_b32_e32 v206, 15, v146
	v_lshrrev_b32_e32 v207, 7, v205
	v_and_b32_e32 v205, 0x7f, v205
	v_add_u32_e32 v207, v207, v206
	v_and_b32_e32 v206, 15, v207
	v_add_u32_e32 v207, 2, v207
	v_and_b32_e32 v207, 15, v207
	v_lshl_or_b32 v206, v206, 7, v205
	v_lshl_or_b32 v207, v207, 7, v205
	v_lshlrev_b32_e32 v204, 11, v204
	v_add_u32_e32 v206, v206, v204
	v_add_u32_e32 v207, v207, v204
	v_cvt_pk_bf16_f32 v188, v124, v125
	v_cvt_pk_bf16_f32 v189, v126, v127
	v_cvt_pk_bf16_f32 v190, v120, v121
	v_cvt_pk_bf16_f32 v191, v122, v123
	global_store_dwordx4 v206, v[188:191], s[64:65]
	v_cvt_pk_bf16_f32 v192, v116, v117
	v_cvt_pk_bf16_f32 v193, v118, v119
	v_cvt_pk_bf16_f32 v194, v112, v113
	v_cvt_pk_bf16_f32 v195, v114, v115
	global_store_dwordx4 v207, v[192:195], s[64:65]
	v_add_u32_e32 v206, 0x8000, v206
	v_add_u32_e32 v207, 0x8000, v207
	v_cvt_pk_bf16_f32 v196, v108, v109
	v_cvt_pk_bf16_f32 v197, v110, v111
	v_cvt_pk_bf16_f32 v198, v104, v105
	v_cvt_pk_bf16_f32 v199, v106, v107
	global_store_dwordx4 v206, v[196:199], s[64:65]
	v_cvt_pk_bf16_f32 v200, v100, v101
	v_cvt_pk_bf16_f32 v201, v102, v103
	v_cvt_pk_bf16_f32 v202, v96, v97
	v_cvt_pk_bf16_f32 v203, v98, v99
	global_store_dwordx4 v207, v[200:203], s[64:65]
	v_add_u32_e32 v206, 0x8000, v206
	v_add_u32_e32 v207, 0x8000, v207
	v_cvt_pk_bf16_f32 v188, v92, v93
	v_cvt_pk_bf16_f32 v189, v94, v95
	v_cvt_pk_bf16_f32 v190, v88, v89
	v_cvt_pk_bf16_f32 v191, v90, v91
	global_store_dwordx4 v206, v[188:191], s[64:65]
	v_cvt_pk_bf16_f32 v192, v84, v85
	v_cvt_pk_bf16_f32 v193, v86, v87
	v_cvt_pk_bf16_f32 v194, v80, v81
	v_cvt_pk_bf16_f32 v195, v82, v83
	global_store_dwordx4 v207, v[192:195], s[64:65]
	v_add_u32_e32 v206, 0x8000, v206
	v_add_u32_e32 v207, 0x8000, v207
	v_cvt_pk_bf16_f32 v196, v76, v77
	v_cvt_pk_bf16_f32 v197, v78, v79
	v_cvt_pk_bf16_f32 v198, v72, v73
	v_cvt_pk_bf16_f32 v199, v74, v75
	global_store_dwordx4 v206, v[196:199], s[64:65]
	v_cvt_pk_bf16_f32 v200, v68, v69
	v_cvt_pk_bf16_f32 v201, v70, v71
	v_cvt_pk_bf16_f32 v202, v64, v65
	v_cvt_pk_bf16_f32 v203, v66, v67
	global_store_dwordx4 v207, v[200:203], s[64:65]
	v_add_u32_e32 v206, 0x28000, v206
	v_add_u32_e32 v207, 0x28000, v207
	v_cvt_pk_bf16_f32 v188, v60, v61
	v_cvt_pk_bf16_f32 v189, v62, v63
	v_cvt_pk_bf16_f32 v190, v56, v57
	v_cvt_pk_bf16_f32 v191, v58, v59
	global_store_dwordx4 v206, v[188:191], s[64:65]
	v_cvt_pk_bf16_f32 v192, v52, v53
	v_cvt_pk_bf16_f32 v193, v54, v55
	v_cvt_pk_bf16_f32 v194, v48, v49
	v_cvt_pk_bf16_f32 v195, v50, v51
	global_store_dwordx4 v207, v[192:195], s[64:65]
	v_add_u32_e32 v206, 0x8000, v206
	v_add_u32_e32 v207, 0x8000, v207
	v_cvt_pk_bf16_f32 v196, v44, v45
	v_cvt_pk_bf16_f32 v197, v46, v47
	v_cvt_pk_bf16_f32 v198, v40, v41
	v_cvt_pk_bf16_f32 v199, v42, v43
	global_store_dwordx4 v206, v[196:199], s[64:65]
	v_cvt_pk_bf16_f32 v200, v36, v37
	v_cvt_pk_bf16_f32 v201, v38, v39
	v_cvt_pk_bf16_f32 v202, v32, v33
	v_cvt_pk_bf16_f32 v203, v34, v35
	global_store_dwordx4 v207, v[200:203], s[64:65]
	v_add_u32_e32 v206, 0x8000, v206
	v_add_u32_e32 v207, 0x8000, v207
	v_cvt_pk_bf16_f32 v188, v28, v29
	v_cvt_pk_bf16_f32 v189, v30, v31
	v_cvt_pk_bf16_f32 v190, v24, v25
	v_cvt_pk_bf16_f32 v191, v26, v27
	global_store_dwordx4 v206, v[188:191], s[64:65]
	v_cvt_pk_bf16_f32 v192, v20, v21
	v_cvt_pk_bf16_f32 v193, v22, v23
	v_cvt_pk_bf16_f32 v194, v16, v17
	v_cvt_pk_bf16_f32 v195, v18, v19
	global_store_dwordx4 v207, v[192:195], s[64:65]
	v_add_u32_e32 v206, 0x8000, v206
	v_add_u32_e32 v207, 0x8000, v207
	v_cvt_pk_bf16_f32 v196, v12, v13
	v_cvt_pk_bf16_f32 v197, v14, v15
	v_cvt_pk_bf16_f32 v198, v8, v9
	v_cvt_pk_bf16_f32 v199, v10, v11
	global_store_dwordx4 v206, v[196:199], s[64:65]
	v_cvt_pk_bf16_f32 v200, v4, v5
	v_cvt_pk_bf16_f32 v201, v6, v7
	v_cvt_pk_bf16_f32 v202, v0, v1
	v_cvt_pk_bf16_f32 v203, v2, v3
	global_store_dwordx4 v207, v[200:203], s[64:65]
	s_and_b64 vcc, exec, s[8:9]
	s_mov_b64 s[8:9], -1
	s_cbranch_vccnz .LBB0_386
	s_andn2_b64 vcc, exec, s[22:23]
	s_cbranch_vccnz .LBB0_385
	s_barrier
	s_branch .LBB0_385
